# RG-LRU final recurrence stage: LDS read batching (all eight ds_read2 up front, counted lgkmcnt waits) instead of four serial LDS round trips; on top of v145
# speedup vs baseline: 1.0044x; 1.0044x over previous
; __device__ __forceinline__ bf16_t f2bf(float f) { return (bf16_t)(cvt_pk_bf16(f, 0.f) & 0xffffu); }
; __device__ __forceinline__ float siluf_(float x) { return x * __builtin_amdgcn_rcpf(1.f + __expf(-x)); }
; __device__ __forceinline__ void rglru_unit(const Params& p, const WS& ws, int j, int u, bool dry = false) {
;     ...
;   auto flush_y = [&]() {
;     if (ypend_t0 >= 0) {
; #pragma unroll
;       for (int i = 0; i < 8; ++i) {
;         const int t = ypend_t0 + 8 * ssg + i;
;         if (t < T_ && !dry) ws.GA[(size_t)(b * T_ + t) * 1024 + 128 * g + 32 * jq + sc] = ypend[i];
;       }
;     }
;   };
;   auto body = [&](int tile, u32x4 (&xin)[4], bf16_t (&gav)[8]) {
;     const int t0 = 64 * tile;
; #pragma unroll
;     for (int i = 0; i < 4; ++i) {
;       const int ci = tid + 256 * i; const int row = ci >> 4, ch = ci & 15;
;       *(u32x4*)(XC + row * 136 + 8 * ch) = xin[i];
;     }
;     ...
;     {
;       float h = hin;
; #pragma unroll
;       for (int i = 0; i < 8; ++i) {
;         const float a = AUa[(8 * ssg + i) * 33 + sc], uu = AUu[(8 * ssg + i) * 33 + sc];
;         h = a * h + uu;
;         const int t = t0 + 8 * ssg + i;
;         ypend[i] = f2bf(h * siluf_(gcur[i]));
;       }
;       if (ssg == 7) CARRY[sc] = h;
;       ypend_t0 = t0;
.LBB0_1460:
	s_or_b64 exec, exec, s[4:5]
	s_waitcnt lgkmcnt(0)
	s_barrier
	ds_read2_b32 v[204:205], v137 offset1:33
	ds_read2_b32 v[56:57], v138 offset0:64 offset1:97
	ds_read2_b32 v[206:207], v137 offset0:66 offset1:99
	ds_read2_b32 v[54:55], v138 offset0:130 offset1:163
	ds_read2_b32 v[208:209], v137 offset0:132 offset1:165
	ds_read2_b32 v[52:53], v138 offset0:196 offset1:229
	ds_read2_b32 v[58:59], v137 offset0:198 offset1:231
	ds_read2_b32 v[244:245], v140 offset0:6 offset1:39
	s_waitcnt lgkmcnt(6)
	v_fma_f32 v56, v13, v204, v56
	v_fmac_f32_e32 v57, v56, v205
	s_waitcnt lgkmcnt(4)
	v_fma_f32 v54, v57, v206, v54
	v_fmac_f32_e32 v55, v54, v207
	s_waitcnt lgkmcnt(2)
	v_fma_f32 v52, v55, v208, v52
	v_fmac_f32_e32 v53, v52, v209
	s_waitcnt lgkmcnt(0)
	v_fma_f32 v13, v53, v58, v244
	v_fma_f32 v15, v13, v59, v245
	s_and_saveexec_b64 s[4:5], s[50:51]
	ds_write_b32 v115, v15 offset:53760
	s_or_b64 exec, exec, s[4:5]
	v_lshlrev_b32_e32 v14, 16, v120
	v_mul_f32_e32 v58, 0xbfb8aa3b, v14
	v_exp_f32_e32 v58, v58
	v_lshlrev_b32_e32 v59, 16, v119
	v_lshlrev_b32_e32 v60, 16, v122
	v_lshlrev_b32_e32 v61, 16, v121
	v_add_f32_e32 v58, 1.0, v58
	v_rcp_f32_e32 v58, v58
	v_lshlrev_b32_e32 v62, 16, v124
	v_lshlrev_b32_e32 v63, 16, v123
	v_lshlrev_b32_e32 v64, 16, v128
	v_mul_f32_e32 v14, v58, v14
	v_mul_f32_e32 v14, v14, v56
	v_cvt_pk_bf16_f32 v58, v14, s0
	v_mul_f32_e32 v14, 0xbfb8aa3b, v59
	v_exp_f32_e32 v14, v14
	v_lshlrev_b32_e32 v65, 16, v127
	s_cmp_gt_u32 s7, 32
	v_add_f32_e32 v14, 1.0, v14
	v_rcp_f32_e32 v14, v14
	s_nop 0
	v_mul_f32_e32 v14, v14, v59
	v_mul_f32_e32 v14, v14, v57
	v_cvt_pk_bf16_f32 v59, v14, s0
	v_mul_f32_e32 v14, 0xbfb8aa3b, v60
	v_exp_f32_e32 v14, v14
	s_nop 0
	v_add_f32_e32 v14, 1.0, v14
	v_rcp_f32_e32 v14, v14
	s_nop 0
	v_mul_f32_e32 v14, v14, v60
	v_mul_f32_e32 v14, v14, v54
	v_cvt_pk_bf16_f32 v56, v14, s0
	v_mul_f32_e32 v14, 0xbfb8aa3b, v61
	v_exp_f32_e32 v14, v14
	s_nop 0
	v_add_f32_e32 v14, 1.0, v14
	v_rcp_f32_e32 v14, v14
	s_nop 0
	v_mul_f32_e32 v14, v14, v61
	v_mul_f32_e32 v14, v14, v55
	v_cvt_pk_bf16_f32 v57, v14, s0
	v_mul_f32_e32 v14, 0xbfb8aa3b, v62
	v_exp_f32_e32 v14, v14
	s_nop 0
	v_add_f32_e32 v14, 1.0, v14
	v_rcp_f32_e32 v14, v14
	s_nop 0
	v_mul_f32_e32 v14, v14, v62
	v_mul_f32_e32 v14, v14, v52
	v_cvt_pk_bf16_f32 v54, v14, s0
	v_mul_f32_e32 v14, 0xbfb8aa3b, v63
	v_exp_f32_e32 v14, v14
	s_nop 0
	v_add_f32_e32 v14, 1.0, v14
	v_rcp_f32_e32 v14, v14
	s_nop 0
	v_mul_f32_e32 v14, v14, v63
	v_mul_f32_e32 v14, v14, v53
	v_cvt_pk_bf16_f32 v55, v14, s0
	v_mul_f32_e32 v14, 0xbfb8aa3b, v64
	v_exp_f32_e32 v14, v14
	s_nop 0
	v_add_f32_e32 v14, 1.0, v14
	v_rcp_f32_e32 v14, v14
	s_nop 0
	v_mul_f32_e32 v14, v14, v64
	v_mul_f32_e32 v13, v14, v13
	v_cvt_pk_bf16_f32 v14, v13, s0
	v_mul_f32_e32 v13, 0xbfb8aa3b, v65
	v_exp_f32_e32 v13, v13
	s_nop 0
	v_add_f32_e32 v13, 1.0, v13
	v_rcp_f32_e32 v13, v13
	s_nop 0
	v_mul_f32_e32 v13, v13, v65
	v_mul_f32_e32 v13, v13, v15
	v_cvt_pk_bf16_f32 v15, v13, s0
	s_cbranch_scc1 .LBB0_1554
	v_add_u32_e32 v60, s6, v83
	v_cmp_gt_i32_e64 s[52:53], s15, v60
	v_add_u32_e32 v52, s6, v69
	s_waitcnt vmcnt(8)
	ds_write_b128 v106, v[36:39]
	ds_write_b128 v107, v[40:43]
	ds_write_b128 v109, v[44:47]
	ds_write_b128 v110, v[48:51]
	s_waitcnt lgkmcnt(0)
	s_barrier
	s_cmpk_gt_i32 s6, 0x7d0
	s_cbranch_scc1 .Lrg_fslow2
	s_mov_b64 s[4:5], 0x1000
	v_ashrrev_i32_e32 v53, 31, v52
	v_lshlrev_b64 v[62:63], 11, v[52:53]
	v_lshl_add_u64 v[62:63], v[74:75], 0, v[62:63]
	global_store_short v[62:63], v58, off
	global_store_short v[62:63], v59, off offset:2048
	v_lshl_add_u64 v[62:63], v[62:63], 0, s[4:5]
	global_store_short v[62:63], v56, off
	global_store_short v[62:63], v57, off offset:2048
	v_lshl_add_u64 v[62:63], v[62:63], 0, s[4:5]
	global_store_short v[62:63], v54, off
	global_store_short v[62:63], v55, off offset:2048
	v_lshl_add_u64 v[62:63], v[62:63], 0, s[4:5]
	global_store_short v[62:63], v14, off
	global_store_short v[62:63], v15, off offset:2048
	s_branch .Lrg_fjoin2

; __device__ __forceinline__ bf16_t f2bf(float f) { return (bf16_t)(cvt_pk_bf16(f, 0.f) & 0xffffu); }
; __device__ __forceinline__ float siluf_(float x) { return x * __builtin_amdgcn_rcpf(1.f + __expf(-x)); }
; __device__ __forceinline__ void rglru_unit(const Params& p, const WS& ws, int j, int u, bool dry = false) {
;     ...
;     {
;       float h = hin;
; #pragma unroll
;       for (int i = 0; i < 8; ++i) {
;         const float a = AUa[(8 * ssg + i) * 33 + sc], uu = AUu[(8 * ssg + i) * 33 + sc];
;         h = a * h + uu;
;         const int t = t0 + 8 * ssg + i;
;         ypend[i] = f2bf(h * siluf_(gcur[i]));
;       }
;       if (ssg == 7) CARRY[sc] = h;
;       ypend_t0 = t0;
.LBB0_1545:
	s_or_b64 exec, exec, s[4:5]
	s_waitcnt lgkmcnt(0)
	s_barrier
	ds_read2_b32 v[204:205], v137 offset1:33
	ds_read2_b32 v[56:57], v138 offset0:64 offset1:97
	ds_read2_b32 v[206:207], v137 offset0:66 offset1:99
	ds_read2_b32 v[54:55], v138 offset0:130 offset1:163
	ds_read2_b32 v[208:209], v137 offset0:132 offset1:165
	ds_read2_b32 v[52:53], v138 offset0:196 offset1:229
	ds_read2_b32 v[58:59], v137 offset0:198 offset1:231
	ds_read2_b32 v[244:245], v140 offset0:6 offset1:39
	s_waitcnt lgkmcnt(6)
	v_fma_f32 v56, v14, v204, v56
	v_fmac_f32_e32 v57, v56, v205
	s_waitcnt lgkmcnt(4)
	v_fma_f32 v54, v57, v206, v54
	v_fmac_f32_e32 v55, v54, v207
	s_waitcnt lgkmcnt(2)
	v_fma_f32 v52, v55, v208, v52
	v_fmac_f32_e32 v53, v52, v209
	s_waitcnt lgkmcnt(0)
	v_fma_f32 v14, v53, v58, v244
	v_fma_f32 v15, v14, v59, v245
	s_and_saveexec_b64 s[4:5], s[50:51]
	ds_write_b32 v115, v15 offset:53760
	s_or_b64 exec, exec, s[4:5]
	v_lshlrev_b32_e32 v58, 16, v86
	v_mul_f32_e32 v66, 0xbfb8aa3b, v58
	v_exp_f32_e32 v66, v66
	v_lshlrev_b32_e32 v59, 16, v85
	v_lshlrev_b32_e32 v60, 16, v88
	v_lshlrev_b32_e32 v61, 16, v87
	v_add_f32_e32 v66, 1.0, v66
	v_rcp_f32_e32 v66, v66
	v_lshlrev_b32_e32 v62, 16, v91
	v_lshlrev_b32_e32 v63, 16, v90
	v_lshlrev_b32_e32 v64, 16, v92
	v_mul_f32_e32 v58, v66, v58
	v_mul_f32_e32 v56, v58, v56
	v_cvt_pk_bf16_f32 v58, v56, s0
	v_mul_f32_e32 v56, 0xbfb8aa3b, v59
	v_exp_f32_e32 v56, v56
	v_lshlrev_b32_e32 v65, 16, v94
	s_add_i32 s4, s6, 64
	v_add_f32_e32 v56, 1.0, v56
	v_rcp_f32_e32 v56, v56
	s_nop 0
	v_mul_f32_e32 v56, v56, v59
	v_mul_f32_e32 v56, v56, v57
	v_cvt_pk_bf16_f32 v59, v56, s0
	v_mul_f32_e32 v56, 0xbfb8aa3b, v60
	v_exp_f32_e32 v56, v56
	s_nop 0
	v_add_f32_e32 v56, 1.0, v56
	v_rcp_f32_e32 v56, v56
	s_nop 0
	v_mul_f32_e32 v56, v56, v60
	v_mul_f32_e32 v54, v56, v54
	v_cvt_pk_bf16_f32 v56, v54, s0
	v_mul_f32_e32 v54, 0xbfb8aa3b, v61
	v_exp_f32_e32 v54, v54
	s_nop 0
	v_add_f32_e32 v54, 1.0, v54
	v_rcp_f32_e32 v54, v54
	s_nop 0
	v_mul_f32_e32 v54, v54, v61
	v_mul_f32_e32 v54, v54, v55
	v_cvt_pk_bf16_f32 v57, v54, s0
	v_mul_f32_e32 v54, 0xbfb8aa3b, v62
	v_exp_f32_e32 v54, v54
	s_nop 0
	v_add_f32_e32 v54, 1.0, v54
	v_rcp_f32_e32 v54, v54
	s_nop 0
	v_mul_f32_e32 v54, v54, v62
	v_mul_f32_e32 v52, v54, v52
	v_cvt_pk_bf16_f32 v54, v52, s0
	v_mul_f32_e32 v52, 0xbfb8aa3b, v63
	v_exp_f32_e32 v52, v52
	s_nop 0
	v_add_f32_e32 v52, 1.0, v52
	v_rcp_f32_e32 v52, v52
	s_nop 0
	v_mul_f32_e32 v52, v52, v63
	v_mul_f32_e32 v52, v52, v53
	v_cvt_pk_bf16_f32 v55, v52, s0
	v_mul_f32_e32 v52, 0xbfb8aa3b, v64
	v_exp_f32_e32 v52, v52
	s_nop 0
	v_add_f32_e32 v52, 1.0, v52
	v_rcp_f32_e32 v52, v52
	s_nop 0
	v_mul_f32_e32 v52, v52, v64
	v_mul_f32_e32 v14, v52, v14
	v_mul_f32_e32 v52, 0xbfb8aa3b, v65
	v_exp_f32_e32 v52, v52
	v_cvt_pk_bf16_f32 v14, v14, s0
	v_add_f32_e32 v52, 1.0, v52
	v_rcp_f32_e32 v52, v52
	s_nop 0
	v_mul_f32_e32 v52, v52, v65
	v_mul_f32_e32 v15, v52, v15
	v_cvt_pk_bf16_f32 v15, v15, s0
	s_branch .LBB0_1555
